# v10: v9 + attention: stash/gain loads of the stream-1 finalization issued together, K fragments prefetched in the tile loop
# baseline (speedup 1.0000x reference)
.LBB0_244:
	s_and_b32 s12, s5, 1
	s_cmp_le_i32 s5, s81
	s_cselect_b64 s[10:11], -1, 0
	s_xor_b32 s13, s12, 1
	v_lshl_add_u64 v[82:83], v[178:179], 0, s[8:9]
	s_mul_i32 s14, s13, 0x2400
	v_add_co_u32_e32 v86, vcc, 0xe0c0000, v82
	v_add_u32_e32 v81, s14, v196
	s_mulk_i32 s13, 0x5000
	v_addc_co_u32_e32 v87, vcc, 0, v83, vcc
	s_waitcnt vmcnt(0)
	ds_write_b128 v81, v[154:157]
	v_add_u32_e32 v81, s13, v198
	v_add_co_u32_e32 v82, vcc, 0xe0e0000, v82
	ds_write_b128 v81, v[158:161] offset:18432
	ds_write_b128 v81, v[162:165] offset:28672
	v_lshl_add_u64 v[84:85], v[182:183], 0, s[8:9]
	v_addc_co_u32_e32 v83, vcc, 0, v83, vcc
	global_load_dwordx4 v[154:157], v[84:85], off
	global_load_dwordx4 v[158:161], v[86:87], off offset:2048
	global_load_dwordx4 v[162:165], v[82:83], off offset:2048
	s_cmp_gt_i32 s5, s81
	s_cbranch_scc1 .LBB0_248
	s_mul_i32 s13, s12, 0x2400
	v_add_u32_e32 v81, s13, v200
	ds_read_b128 v[224:227], v81
	ds_read_b128 v[228:231], v81 offset:4608
	ds_read_b128 v[232:235], v81 offset:32
	ds_read_b128 v[236:239], v81 offset:4640
	ds_read_b128 v[240:243], v81 offset:64
	ds_read_b128 v[184:187], v81 offset:4672
	s_waitcnt lgkmcnt(5)
	v_mfma_f32_32x32x16_bf16 v[82:97], v[224:227], v[150:153], v[64:79]
	ds_read_b128 v[224:227], v81 offset:96
	s_waitcnt lgkmcnt(5)
	v_mfma_f32_32x32x16_bf16 v[98:113], v[228:231], v[150:153], v[64:79]
	ds_read_b128 v[228:231], v81 offset:4704
	s_waitcnt lgkmcnt(5)
	v_mfma_f32_32x32x16_bf16 v[82:97], v[232:235], v[146:149], v[82:97]
	s_waitcnt lgkmcnt(4)
	v_mfma_f32_32x32x16_bf16 v[98:113], v[236:239], v[146:149], v[98:113]
	s_waitcnt lgkmcnt(3)
	v_mfma_f32_32x32x16_bf16 v[82:97], v[240:243], v[142:145], v[82:97]
	s_waitcnt lgkmcnt(2)
	v_mfma_f32_32x32x16_bf16 v[98:113], v[184:187], v[142:145], v[98:113]
	s_waitcnt lgkmcnt(1)
	v_mfma_f32_32x32x16_bf16 v[82:97], v[224:227], v[138:141], v[82:97]
	s_waitcnt lgkmcnt(0)
	v_mfma_f32_32x32x16_bf16 v[98:113], v[228:231], v[138:141], v[98:113]
	s_nop 0
	s_nop 8
	v_exp_f32_e32 v184, v82
	v_exp_f32_e32 v185, v83
	v_exp_f32_e32 v186, v84
	v_exp_f32_e32 v187, v85
	v_exp_f32_e32 v82, v98
	v_exp_f32_e32 v83, v99
	v_exp_f32_e32 v84, v100
	v_exp_f32_e32 v85, v101
	v_add_f32_e32 v81, v184, v82
	v_exp_f32_e32 v101, v86
	v_exp_f32_e32 v189, v102
	v_exp_f32_e32 v100, v87
	v_exp_f32_e32 v188, v103
	v_add_f32_e32 v81, 0, v81
	v_add_f32_e32 v98, v185, v83
	v_add_f32_e32 v81, v98, v81
	v_add_f32_e32 v98, v186, v84
	v_exp_f32_e32 v103, v88
	v_exp_f32_e32 v87, v104
	v_exp_f32_e32 v102, v89
	v_exp_f32_e32 v86, v105
	v_add_f32_e32 v81, v98, v81
	v_add_f32_e32 v98, v187, v85
	v_add_f32_e32 v81, v98, v81
	v_pk_add_f32 v[88:89], v[100:101], v[188:189]
	v_exp_f32_e32 v105, v90
	v_add_f32_e32 v81, v89, v81
	v_add_f32_e32 v81, v88, v81
	v_pk_add_f32 v[88:89], v[102:103], v[86:87]
	v_exp_f32_e32 v104, v91
	v_add_f32_e32 v81, v89, v81
	v_add_f32_e32 v81, v88, v81
	v_exp_f32_e32 v89, v106
	v_exp_f32_e32 v88, v107
	v_exp_f32_e32 v107, v92
	v_exp_f32_e32 v91, v108
	v_exp_f32_e32 v106, v93
	v_exp_f32_e32 v90, v109
	v_pk_add_f32 v[92:93], v[104:105], v[88:89]
	v_exp_f32_e32 v109, v94
	v_add_f32_e32 v81, v93, v81
	v_add_f32_e32 v81, v92, v81
	v_pk_add_f32 v[92:93], v[106:107], v[90:91]
	v_exp_f32_e32 v108, v95
	v_add_f32_e32 v81, v93, v81
	v_add_f32_e32 v81, v92, v81
	v_exp_f32_e32 v93, v110
	v_exp_f32_e32 v92, v111
	v_exp_f32_e32 v111, v96
	v_exp_f32_e32 v95, v112
	v_exp_f32_e32 v110, v97
	v_exp_f32_e32 v94, v113
	v_pk_add_f32 v[96:97], v[108:109], v[92:93]
	s_nop 0
	v_add_f32_e32 v81, v97, v81
	v_add_f32_e32 v81, v96, v81
	v_pk_add_f32 v[96:97], v[110:111], v[94:95]
	s_nop 0
	v_add_f32_e32 v81, v97, v81
	v_add_f32_e32 v180, v96, v81
	v_cmp_ngt_f32_e32 vcc, s23, v180
	s_cbranch_vccz .LBB0_247
	ds_bpermute_b32 v64, v214, v180
	v_mov_b32_e32 v97, v100
	v_mov_b32_e32 v100, v103
	v_mov_b32_e32 v103, v86
	v_mov_b32_e32 v86, v105
	s_waitcnt lgkmcnt(0)
	v_add_f32_e32 v64, v180, v64
	v_min_f32_e32 v64, 0x7f61b1e6, v64
	v_log_f32_e32 v64, v64
	v_mov_b32_e32 v105, v88
	v_mov_b32_e32 v88, v107
	v_mov_b32_e32 v107, v90
	v_floor_f32_e32 v64, v64
	v_max_f32_e32 v64, 0, v64
	v_mov_b32_e32 v90, v109
	v_mov_b32_e32 v109, v92
	v_mov_b32_e32 v92, v111
	v_mov_b32_e32 v111, v94
	v_exp_f32_e64 v94, -v64
	v_mov_b32_e32 v96, v101
	v_mov_b32_e32 v98, v189
	v_mov_b32_e32 v99, v188
	v_mov_b32_e32 v101, v102
	v_mov_b32_e32 v102, v87
	v_mov_b32_e32 v87, v104
	v_mov_b32_e32 v104, v89
	v_mov_b32_e32 v89, v106
	v_mov_b32_e32 v106, v91
	v_mov_b32_e32 v91, v108
	v_mov_b32_e32 v108, v93
	v_mov_b32_e32 v93, v110
	v_mov_b32_e32 v110, v95
	v_add_f32_e32 v80, v80, v64
	v_xor_b32_e32 v64, 0x80000000, v80
	v_pk_mul_f32 v[110:111], v[110:111], v[94:95] op_sel_hi:[1,0]
	v_pk_mul_f32 v[108:109], v[108:109], v[94:95] op_sel_hi:[1,0]
	v_pk_mul_f32 v[106:107], v[106:107], v[94:95] op_sel_hi:[1,0]
	v_pk_mul_f32 v[104:105], v[104:105], v[94:95] op_sel_hi:[1,0]
	v_pk_mul_f32 v[102:103], v[102:103], v[94:95] op_sel_hi:[1,0]
	v_pk_mul_f32 v[98:99], v[98:99], v[94:95] op_sel_hi:[1,0]
	v_pk_mul_f32 v[112:113], v[92:93], v[94:95] op_sel_hi:[1,0]
	v_pk_mul_f32 v[216:217], v[90:91], v[94:95] op_sel_hi:[1,0]
	v_pk_mul_f32 v[218:219], v[88:89], v[94:95] op_sel_hi:[1,0]
	v_pk_mul_f32 v[220:221], v[86:87], v[94:95] op_sel_hi:[1,0]
	v_pk_mul_f32 v[222:223], v[100:101], v[94:95] op_sel_hi:[1,0]
	v_pk_mul_f32 v[96:97], v[96:97], v[94:95] op_sel_hi:[1,0]
	v_mov_b32_e32 v65, v64
	v_mov_b32_e32 v66, v64
	v_mov_b32_e32 v67, v64
	v_mov_b32_e32 v68, v64
	v_mov_b32_e32 v69, v64
	v_mov_b32_e32 v70, v64
	v_mov_b32_e32 v71, v64
	v_mov_b32_e32 v72, v64
	v_mov_b32_e32 v73, v64
	v_mov_b32_e32 v74, v64
	v_mov_b32_e32 v75, v64
	v_mov_b32_e32 v76, v64
	v_mov_b32_e32 v77, v64
	v_mov_b32_e32 v78, v64
	v_mov_b32_e32 v79, v64
	v_pk_mul_f32 v[84:85], v[84:85], v[94:95] op_sel_hi:[1,0]
	v_pk_mul_f32 v[82:83], v[82:83], v[94:95] op_sel_hi:[1,0]
	v_pk_mul_f32 v[14:15], v[14:15], v[94:95] op_sel_hi:[1,0]
	v_pk_mul_f32 v[12:13], v[12:13], v[94:95] op_sel_hi:[1,0]
	v_pk_mul_f32 v[10:11], v[10:11], v[94:95] op_sel_hi:[1,0]
	v_pk_mul_f32 v[8:9], v[8:9], v[94:95] op_sel_hi:[1,0]
	v_pk_mul_f32 v[6:7], v[6:7], v[94:95] op_sel_hi:[1,0]
	v_pk_mul_f32 v[4:5], v[4:5], v[94:95] op_sel_hi:[1,0]
	v_pk_mul_f32 v[2:3], v[2:3], v[94:95] op_sel_hi:[1,0]
	v_pk_mul_f32 v[0:1], v[0:1], v[94:95] op_sel_hi:[1,0]
	v_pk_mul_f32 v[46:47], v[46:47], v[94:95] op_sel_hi:[1,0]
	v_pk_mul_f32 v[44:45], v[44:45], v[94:95] op_sel_hi:[1,0]
	v_pk_mul_f32 v[42:43], v[42:43], v[94:95] op_sel_hi:[1,0]
	v_pk_mul_f32 v[40:41], v[40:41], v[94:95] op_sel_hi:[1,0]
	v_pk_mul_f32 v[38:39], v[38:39], v[94:95] op_sel_hi:[1,0]
	v_pk_mul_f32 v[36:37], v[36:37], v[94:95] op_sel_hi:[1,0]
	v_pk_mul_f32 v[34:35], v[34:35], v[94:95] op_sel_hi:[1,0]
	v_pk_mul_f32 v[32:33], v[32:33], v[94:95] op_sel_hi:[1,0]
	v_pk_mul_f32 v[30:31], v[30:31], v[94:95] op_sel_hi:[1,0]
	v_pk_mul_f32 v[28:29], v[28:29], v[94:95] op_sel_hi:[1,0]
	v_pk_mul_f32 v[26:27], v[26:27], v[94:95] op_sel_hi:[1,0]
	v_pk_mul_f32 v[24:25], v[24:25], v[94:95] op_sel_hi:[1,0]
	v_pk_mul_f32 v[22:23], v[22:23], v[94:95] op_sel_hi:[1,0]
	v_pk_mul_f32 v[20:21], v[20:21], v[94:95] op_sel_hi:[1,0]
	v_pk_mul_f32 v[18:19], v[18:19], v[94:95] op_sel_hi:[1,0]
	v_pk_mul_f32 v[16:17], v[16:17], v[94:95] op_sel_hi:[1,0]
	v_pk_mul_f32 v[62:63], v[62:63], v[94:95] op_sel_hi:[1,0]
	v_pk_mul_f32 v[60:61], v[60:61], v[94:95] op_sel_hi:[1,0]
	v_pk_mul_f32 v[58:59], v[58:59], v[94:95] op_sel_hi:[1,0]
	v_pk_mul_f32 v[56:57], v[56:57], v[94:95] op_sel_hi:[1,0]
	v_pk_mul_f32 v[54:55], v[54:55], v[94:95] op_sel_hi:[1,0]
	v_pk_mul_f32 v[52:53], v[52:53], v[94:95] op_sel_hi:[1,0]
	v_pk_mul_f32 v[50:51], v[50:51], v[94:95] op_sel_hi:[1,0]
	v_pk_mul_f32 v[48:49], v[48:49], v[94:95] op_sel_hi:[1,0]
	v_pk_mul_f32 v[186:187], v[186:187], v[94:95] op_sel_hi:[1,0]
	v_pk_mul_f32 v[184:185], v[184:185], v[94:95] op_sel_hi:[1,0]
	v_pk_mul_f32 v[180:181], v[180:181], v[94:95] op_sel_hi:[1,0]
	v_mov_b32_e32 v189, v98
	v_mov_b32_e32 v188, v99
	v_mov_b32_e32 v87, v102
	v_mov_b32_e32 v86, v103
	v_mov_b32_e32 v89, v104
	v_mov_b32_e32 v88, v105
	v_mov_b32_e32 v91, v106
	v_mov_b32_e32 v90, v107
	v_mov_b32_e32 v93, v108
	v_mov_b32_e32 v92, v109
	v_mov_b32_e32 v95, v110
	v_mov_b32_e32 v94, v111
	v_mov_b32_e32 v101, v96
	v_mov_b32_e32 v100, v97
	v_mov_b32_e32 v103, v222
	v_mov_b32_e32 v102, v223
	v_mov_b32_e32 v105, v220
	v_mov_b32_e32 v104, v221
	v_mov_b32_e32 v107, v218
	v_mov_b32_e32 v106, v219
	v_mov_b32_e32 v109, v216
	v_mov_b32_e32 v108, v217
	v_mov_b32_e32 v111, v112
	v_mov_b32_e32 v110, v113

.LBB0_264:
	global_load_dwordx4 v[56:59], v[170:171], off
	global_load_dwordx4 v[60:63], v[170:171], off offset:16
	global_load_dwordx4 v[72:75], v[170:171], off offset:32
	global_load_dwordx4 v[76:79], v[170:171], off offset:48
	global_load_dwordx4 v[80:83], v[170:171], off offset:64
	global_load_dwordx4 v[84:87], v[170:171], off offset:80
	global_load_dwordx4 v[88:91], v[170:171], off offset:96
	global_load_dwordx4 v[92:95], v[170:171], off offset:112
	global_load_dwordx4 v[138:141], v[170:171], off offset:128
	global_load_dwordx4 v[142:145], v[170:171], off offset:144
	global_load_dwordx4 v[146:149], v[170:171], off offset:160
	global_load_dwordx4 v[150:153], v[170:171], off offset:176
	global_load_dwordx4 v[154:157], v[170:171], off offset:192
	global_load_dwordx4 v[158:161], v[170:171], off offset:208
	global_load_dwordx4 v[162:165], v[170:171], off offset:224
	global_load_dwordx4 v[180:183], v[170:171], off offset:240
	v_mov_b32_e32 v96, 0
	s_waitcnt vmcnt(15)
	v_fma_f32 v56, -v190, v0, v56
	v_fma_f32 v57, -v190, v1, v57
	v_fma_f32 v58, -v190, v2, v58
	v_fma_f32 v59, -v190, v3, v59
	v_fmac_f32_e32 v96, v56, v56
	v_fmac_f32_e32 v96, v57, v57
	v_fmac_f32_e32 v96, v58, v58
	v_fmac_f32_e32 v96, v59, v59
	global_load_dwordx4 v[0:3], v[172:173], off
	s_waitcnt vmcnt(15)
	v_fma_f32 v60, -v190, v4, v60
	v_fma_f32 v61, -v190, v5, v61
	v_fma_f32 v62, -v190, v6, v62
	v_fma_f32 v63, -v190, v7, v63
	v_fmac_f32_e32 v96, v60, v60
	v_fmac_f32_e32 v96, v61, v61
	v_fmac_f32_e32 v96, v62, v62
	v_fmac_f32_e32 v96, v63, v63
	global_load_dwordx4 v[4:7], v[172:173], off offset:32
	s_waitcnt vmcnt(15)
	v_fma_f32 v72, -v190, v64, v72
	v_fma_f32 v73, -v190, v65, v73
	v_fma_f32 v74, -v190, v66, v74
	v_fma_f32 v75, -v190, v67, v75
	v_fmac_f32_e32 v96, v72, v72
	v_fmac_f32_e32 v96, v73, v73
	v_fmac_f32_e32 v96, v74, v74
	v_fmac_f32_e32 v96, v75, v75
	global_load_dwordx4 v[64:67], v[172:173], off offset:64
	s_waitcnt vmcnt(15)
	v_fma_f32 v76, -v190, v68, v76
	v_fma_f32 v77, -v190, v69, v77
	v_fma_f32 v78, -v190, v70, v78
	v_fma_f32 v79, -v190, v71, v79
	v_fmac_f32_e32 v96, v76, v76
	v_fmac_f32_e32 v96, v77, v77
	v_fmac_f32_e32 v96, v78, v78
	v_fmac_f32_e32 v96, v79, v79
	global_load_dwordx4 v[68:71], v[172:173], off offset:96
	s_waitcnt vmcnt(15)
	v_fma_f32 v80, -v190, v8, v80
	v_fma_f32 v81, -v190, v9, v81
	v_fma_f32 v82, -v190, v10, v82
	v_fma_f32 v83, -v190, v11, v83
	v_fmac_f32_e32 v96, v80, v80
	v_fmac_f32_e32 v96, v81, v81
	v_fmac_f32_e32 v96, v82, v82
	v_fmac_f32_e32 v96, v83, v83
	global_load_dwordx4 v[8:11], v[172:173], off offset:128
	s_waitcnt vmcnt(15)
	v_fma_f32 v84, -v190, v12, v84
	v_fma_f32 v85, -v190, v13, v85
	v_fma_f32 v86, -v190, v14, v86
	v_fma_f32 v87, -v190, v15, v87
	v_fmac_f32_e32 v96, v84, v84
	v_fmac_f32_e32 v96, v85, v85
	v_fmac_f32_e32 v96, v86, v86
	v_fmac_f32_e32 v96, v87, v87
	global_load_dwordx4 v[12:15], v[172:173], off offset:160
	s_waitcnt vmcnt(15)
	v_fma_f32 v88, -v190, v32, v88
	v_fma_f32 v89, -v190, v33, v89
	v_fma_f32 v90, -v190, v34, v90
	v_fma_f32 v91, -v190, v35, v91
	v_fmac_f32_e32 v96, v88, v88
	v_fmac_f32_e32 v96, v89, v89
	v_fmac_f32_e32 v96, v90, v90
	v_fmac_f32_e32 v96, v91, v91
	global_load_dwordx4 v[32:35], v[172:173], off offset:192
	s_waitcnt vmcnt(15)
	v_fma_f32 v92, -v190, v36, v92
	v_fma_f32 v93, -v190, v37, v93
	v_fma_f32 v94, -v190, v38, v94
	v_fma_f32 v95, -v190, v39, v95
	v_fmac_f32_e32 v96, v92, v92
	v_fmac_f32_e32 v96, v93, v93
	v_fmac_f32_e32 v96, v94, v94
	v_fmac_f32_e32 v96, v95, v95
	global_load_dwordx4 v[36:39], v[172:173], off offset:224
	s_waitcnt vmcnt(15)
	v_fma_f32 v138, -v190, v16, v138
	v_fma_f32 v139, -v190, v17, v139
	v_fma_f32 v140, -v190, v18, v140
	v_fma_f32 v141, -v190, v19, v141
	v_fmac_f32_e32 v96, v138, v138
	v_fmac_f32_e32 v96, v139, v139
	v_fmac_f32_e32 v96, v140, v140
	v_fmac_f32_e32 v96, v141, v141
	global_load_dwordx4 v[16:19], v[172:173], off offset:256
	s_waitcnt vmcnt(15)
	v_fma_f32 v142, -v190, v20, v142
	v_fma_f32 v143, -v190, v21, v143
	v_fma_f32 v144, -v190, v22, v144
	v_fma_f32 v145, -v190, v23, v145
	v_fmac_f32_e32 v96, v142, v142
	v_fmac_f32_e32 v96, v143, v143
	v_fmac_f32_e32 v96, v144, v144
	v_fmac_f32_e32 v96, v145, v145
	global_load_dwordx4 v[20:23], v[172:173], off offset:288
	s_waitcnt vmcnt(15)
	v_fma_f32 v146, -v190, v24, v146
	v_fma_f32 v147, -v190, v25, v147
	v_fma_f32 v148, -v190, v26, v148
	v_fma_f32 v149, -v190, v27, v149
	v_fmac_f32_e32 v96, v146, v146
	v_fmac_f32_e32 v96, v147, v147
	v_fmac_f32_e32 v96, v148, v148
	v_fmac_f32_e32 v96, v149, v149
	global_load_dwordx4 v[24:27], v[172:173], off offset:320
	s_waitcnt vmcnt(15)
	v_fma_f32 v150, -v190, v40, v150
	v_fma_f32 v151, -v190, v41, v151
	v_fma_f32 v152, -v190, v42, v152
	v_fma_f32 v153, -v190, v43, v153
	v_fmac_f32_e32 v96, v150, v150
	v_fmac_f32_e32 v96, v151, v151
	v_fmac_f32_e32 v96, v152, v152
	v_fmac_f32_e32 v96, v153, v153
	global_load_dwordx4 v[40:43], v[172:173], off offset:352
	s_waitcnt vmcnt(15)
	v_fma_f32 v154, -v190, v28, v154
	v_fma_f32 v155, -v190, v29, v155
	v_fma_f32 v156, -v190, v30, v156
	v_fma_f32 v157, -v190, v31, v157
	v_fmac_f32_e32 v96, v154, v154
	v_fmac_f32_e32 v96, v155, v155
	v_fmac_f32_e32 v96, v156, v156
	v_fmac_f32_e32 v96, v157, v157
	global_load_dwordx4 v[28:31], v[172:173], off offset:384
	s_waitcnt vmcnt(15)
	v_fma_f32 v158, -v190, v44, v158
	v_fma_f32 v159, -v190, v45, v159
	v_fma_f32 v160, -v190, v46, v160
	v_fma_f32 v161, -v190, v47, v161
	v_fmac_f32_e32 v96, v158, v158
	v_fmac_f32_e32 v96, v159, v159
	v_fmac_f32_e32 v96, v160, v160
	v_fmac_f32_e32 v96, v161, v161
	global_load_dwordx4 v[44:47], v[172:173], off offset:416
	s_waitcnt vmcnt(15)
	v_fma_f32 v162, -v190, v48, v162
	v_fma_f32 v163, -v190, v49, v163
	v_fma_f32 v164, -v190, v50, v164
	v_fma_f32 v165, -v190, v51, v165
	v_fmac_f32_e32 v96, v162, v162
	v_fmac_f32_e32 v96, v163, v163
	v_fmac_f32_e32 v96, v164, v164
	v_fmac_f32_e32 v96, v165, v165
	global_load_dwordx4 v[48:51], v[172:173], off offset:448
	s_waitcnt vmcnt(15)
	v_fma_f32 v180, -v190, v52, v180
	v_fma_f32 v181, -v190, v53, v181
	v_fma_f32 v182, -v190, v54, v182
	v_fma_f32 v183, -v190, v55, v183
	v_fmac_f32_e32 v96, v180, v180
	v_fmac_f32_e32 v96, v181, v181
	v_fmac_f32_e32 v96, v182, v182
	v_fmac_f32_e32 v96, v183, v183
	global_load_dwordx4 v[52:55], v[172:173], off offset:480
	ds_bpermute_b32 v97, v214, v96
	s_waitcnt lgkmcnt(0)
	v_add_f32_e32 v96, v96, v97
	v_fmamk_f32 v96, v96, 0x3c000000, v194
	v_rsq_f32_e32 v96, v96
	s_nop 0
	v_mul_f32_e32 v96, v191, v96
	s_waitcnt vmcnt(15)
	v_mul_f32_e32 v56, v56, v96
	v_mul_f32_e32 v57, v57, v96
	v_mul_f32_e32 v58, v58, v96
	v_mul_f32_e32 v59, v59, v96
	v_mul_f32_e32 v56, v0, v56
	v_mul_f32_e32 v57, v1, v57
	v_mul_f32_e32 v58, v2, v58
	v_mul_f32_e32 v59, v3, v59
	v_cvt_pk_bf16_f32 v56, v56, v57
	v_cvt_pk_bf16_f32 v57, v58, v59
	global_store_dwordx2 v[174:175], v[56:57], off
	s_waitcnt vmcnt(15)
	v_mul_f32_e32 v60, v60, v96
	v_mul_f32_e32 v61, v61, v96
	v_mul_f32_e32 v62, v62, v96
	v_mul_f32_e32 v63, v63, v96
	v_mul_f32_e32 v60, v4, v60
	v_mul_f32_e32 v61, v5, v61
	v_mul_f32_e32 v62, v6, v62
	v_mul_f32_e32 v63, v7, v63
	v_cvt_pk_bf16_f32 v60, v60, v61
	v_cvt_pk_bf16_f32 v61, v62, v63
	global_store_dwordx2 v[174:175], v[60:61], off offset:16
	s_waitcnt vmcnt(15)
	v_mul_f32_e32 v72, v72, v96
	v_mul_f32_e32 v73, v73, v96
	v_mul_f32_e32 v74, v74, v96
	v_mul_f32_e32 v75, v75, v96
	v_mul_f32_e32 v72, v64, v72
	v_mul_f32_e32 v73, v65, v73
	v_mul_f32_e32 v74, v66, v74
	v_mul_f32_e32 v75, v67, v75
	v_cvt_pk_bf16_f32 v72, v72, v73
	v_cvt_pk_bf16_f32 v73, v74, v75
	global_store_dwordx2 v[174:175], v[72:73], off offset:32
	s_waitcnt vmcnt(15)
	v_mul_f32_e32 v76, v76, v96
	v_mul_f32_e32 v77, v77, v96
	v_mul_f32_e32 v78, v78, v96
	v_mul_f32_e32 v79, v79, v96
	v_mul_f32_e32 v76, v68, v76
	v_mul_f32_e32 v77, v69, v77
	v_mul_f32_e32 v78, v70, v78
	v_mul_f32_e32 v79, v71, v79
	v_cvt_pk_bf16_f32 v76, v76, v77
	v_cvt_pk_bf16_f32 v77, v78, v79
	global_store_dwordx2 v[174:175], v[76:77], off offset:48
	s_waitcnt vmcnt(15)
	v_mul_f32_e32 v80, v80, v96
	v_mul_f32_e32 v81, v81, v96
	v_mul_f32_e32 v82, v82, v96
	v_mul_f32_e32 v83, v83, v96
	v_mul_f32_e32 v80, v8, v80
	v_mul_f32_e32 v81, v9, v81
	v_mul_f32_e32 v82, v10, v82
	v_mul_f32_e32 v83, v11, v83
	v_cvt_pk_bf16_f32 v80, v80, v81
	v_cvt_pk_bf16_f32 v81, v82, v83
	global_store_dwordx2 v[174:175], v[80:81], off offset:64
	s_waitcnt vmcnt(15)
	v_mul_f32_e32 v84, v84, v96
	v_mul_f32_e32 v85, v85, v96
	v_mul_f32_e32 v86, v86, v96
	v_mul_f32_e32 v87, v87, v96
	v_mul_f32_e32 v84, v12, v84
	v_mul_f32_e32 v85, v13, v85
	v_mul_f32_e32 v86, v14, v86
	v_mul_f32_e32 v87, v15, v87
	v_cvt_pk_bf16_f32 v84, v84, v85
	v_cvt_pk_bf16_f32 v85, v86, v87
	global_store_dwordx2 v[174:175], v[84:85], off offset:80
	s_waitcnt vmcnt(15)
	v_mul_f32_e32 v88, v88, v96
	v_mul_f32_e32 v89, v89, v96
	v_mul_f32_e32 v90, v90, v96
	v_mul_f32_e32 v91, v91, v96
	v_mul_f32_e32 v88, v32, v88
	v_mul_f32_e32 v89, v33, v89
	v_mul_f32_e32 v90, v34, v90
	v_mul_f32_e32 v91, v35, v91
	v_cvt_pk_bf16_f32 v88, v88, v89
	v_cvt_pk_bf16_f32 v89, v90, v91
	global_store_dwordx2 v[174:175], v[88:89], off offset:96
	s_waitcnt vmcnt(15)
	v_mul_f32_e32 v92, v92, v96
	v_mul_f32_e32 v93, v93, v96
	v_mul_f32_e32 v94, v94, v96
	v_mul_f32_e32 v95, v95, v96
	v_mul_f32_e32 v92, v36, v92
	v_mul_f32_e32 v93, v37, v93
	v_mul_f32_e32 v94, v38, v94
	v_mul_f32_e32 v95, v39, v95
	v_cvt_pk_bf16_f32 v92, v92, v93
	v_cvt_pk_bf16_f32 v93, v94, v95
	global_store_dwordx2 v[174:175], v[92:93], off offset:112
	s_waitcnt vmcnt(15)
	v_mul_f32_e32 v138, v138, v96
	v_mul_f32_e32 v139, v139, v96
	v_mul_f32_e32 v140, v140, v96
	v_mul_f32_e32 v141, v141, v96
	v_mul_f32_e32 v138, v16, v138
	v_mul_f32_e32 v139, v17, v139
	v_mul_f32_e32 v140, v18, v140
	v_mul_f32_e32 v141, v19, v141
	v_cvt_pk_bf16_f32 v138, v138, v139
	v_cvt_pk_bf16_f32 v139, v140, v141
	global_store_dwordx2 v[174:175], v[138:139], off offset:128
	s_waitcnt vmcnt(15)
	v_mul_f32_e32 v142, v142, v96
	v_mul_f32_e32 v143, v143, v96
	v_mul_f32_e32 v144, v144, v96
	v_mul_f32_e32 v145, v145, v96
	v_mul_f32_e32 v142, v20, v142
	v_mul_f32_e32 v143, v21, v143
	v_mul_f32_e32 v144, v22, v144
	v_mul_f32_e32 v145, v23, v145
	v_cvt_pk_bf16_f32 v142, v142, v143
	v_cvt_pk_bf16_f32 v143, v144, v145
	global_store_dwordx2 v[174:175], v[142:143], off offset:144
	s_waitcnt vmcnt(15)
	v_mul_f32_e32 v146, v146, v96
	v_mul_f32_e32 v147, v147, v96
	v_mul_f32_e32 v148, v148, v96
	v_mul_f32_e32 v149, v149, v96
	v_mul_f32_e32 v146, v24, v146
	v_mul_f32_e32 v147, v25, v147
	v_mul_f32_e32 v148, v26, v148
	v_mul_f32_e32 v149, v27, v149
	v_cvt_pk_bf16_f32 v146, v146, v147
	v_cvt_pk_bf16_f32 v147, v148, v149
	global_store_dwordx2 v[174:175], v[146:147], off offset:160
	s_waitcnt vmcnt(15)
	v_mul_f32_e32 v150, v150, v96
	v_mul_f32_e32 v151, v151, v96
	v_mul_f32_e32 v152, v152, v96
	v_mul_f32_e32 v153, v153, v96
	v_mul_f32_e32 v150, v40, v150
	v_mul_f32_e32 v151, v41, v151
	v_mul_f32_e32 v152, v42, v152
	v_mul_f32_e32 v153, v43, v153
	v_cvt_pk_bf16_f32 v150, v150, v151
	v_cvt_pk_bf16_f32 v151, v152, v153
	global_store_dwordx2 v[174:175], v[150:151], off offset:176
	s_waitcnt vmcnt(15)
	v_mul_f32_e32 v154, v154, v96
	v_mul_f32_e32 v155, v155, v96
	v_mul_f32_e32 v156, v156, v96
	v_mul_f32_e32 v157, v157, v96
	v_mul_f32_e32 v154, v28, v154
	v_mul_f32_e32 v155, v29, v155
	v_mul_f32_e32 v156, v30, v156
	v_mul_f32_e32 v157, v31, v157
	v_cvt_pk_bf16_f32 v154, v154, v155
	v_cvt_pk_bf16_f32 v155, v156, v157
	global_store_dwordx2 v[174:175], v[154:155], off offset:192
	s_waitcnt vmcnt(15)
	v_mul_f32_e32 v158, v158, v96
	v_mul_f32_e32 v159, v159, v96
	v_mul_f32_e32 v160, v160, v96
	v_mul_f32_e32 v161, v161, v96
	v_mul_f32_e32 v158, v44, v158
	v_mul_f32_e32 v159, v45, v159
	v_mul_f32_e32 v160, v46, v160
	v_mul_f32_e32 v161, v47, v161
	v_cvt_pk_bf16_f32 v158, v158, v159
	v_cvt_pk_bf16_f32 v159, v160, v161
	global_store_dwordx2 v[174:175], v[158:159], off offset:208
	s_waitcnt vmcnt(15)
	v_mul_f32_e32 v162, v162, v96
	v_mul_f32_e32 v163, v163, v96
	v_mul_f32_e32 v164, v164, v96
	v_mul_f32_e32 v165, v165, v96
	v_mul_f32_e32 v162, v48, v162
	v_mul_f32_e32 v163, v49, v163
	v_mul_f32_e32 v164, v50, v164
	v_mul_f32_e32 v165, v51, v165
	v_cvt_pk_bf16_f32 v162, v162, v163
	v_cvt_pk_bf16_f32 v163, v164, v165
	global_store_dwordx2 v[174:175], v[162:163], off offset:224
	s_waitcnt vmcnt(15)
	v_mul_f32_e32 v180, v180, v96
	v_mul_f32_e32 v181, v181, v96
	v_mul_f32_e32 v182, v182, v96
	v_mul_f32_e32 v183, v183, v96
	v_mul_f32_e32 v180, v52, v180
	v_mul_f32_e32 v181, v53, v181
	v_mul_f32_e32 v182, v54, v182
	v_mul_f32_e32 v183, v55, v183
	v_cvt_pk_bf16_f32 v180, v180, v181
	v_cvt_pk_bf16_f32 v181, v182, v183
	global_store_dwordx2 v[174:175], v[180:181], off offset:240
	s_cbranch_execnz .LBB0_233
